# speedup vs baseline: 1.0360x; 1.0001x over previous
; #define KSWZ(row, colB) ((row) * 256 + ((colB) ^ (KSWZF(row) << 4)))
; #define SBAR() __builtin_amdgcn_sched_barrier(0)
; template <int H> __device__ __forceinline__ void qkt_half(f32x16& pz, const char* Ks, const bf16x8* qr, int r32, int hi) {
;   bf16x8 kf[8];
; #pragma unroll
;   for (int d0 = 0; d0 < 8; ++d0) { const int cb = (d0 * 16 + hi * 8) * 2; kf[d0] = *reinterpret_cast<const bf16x8*>(Ks + KSWZ(32 * H + r32, cb)); }
;   asm volatile("s_waitcnt lgkmcnt(0)" ::: "memory"); SBAR();
;   f32x16 pb = {};
; #pragma unroll
;   for (int d0 = 0; d0 < 8; d0 += 2) {
;     pz = __builtin_amdgcn_mfma_f32_32x32x16_bf16(kf[d0], qr[d0], pz, 0, 0, 0);
;     pb = __builtin_amdgcn_mfma_f32_32x32x16_bf16(kf[d0 + 1], qr[d0 + 1], pb, 0, 0, 0); }
; #pragma unroll
;   for (int r = 0; r < 16; ++r) pz[r] += pb[r];
; }
; template <bool MASK, int H> __device__ __forceinline__ void bias_exp_half(f32x16& pz, float C, float A1, float B1, int lo, int hl, float off) {
; #pragma unroll
;   for (int r = 0; r < 16; ++r) {
;     const int c0 = (r & 3) + 8 * (r >> 2) + 32 * H;
;     float s0 = fmaf(pz[r], C, fmaf(A1, (float)c0, B1)) - off;
;     if (MASK) s0 = (c0 > lo && c0 <= hl) ? s0 : -INFINITY;
;     pz[r] = __builtin_amdgcn_exp2f(s0);
;   }
; }
.LBB0_278:
	v_cvt_f32_i32_e32 v68, v158
	v_ashrrev_i32_e32 v69, 4, v157
	v_sub_u32_e32 v160, v69, v145
	v_fma_f32 v159, v143, v68, v146
	v_cmp_lt_i32_e32 vcc, 62, v160
	s_nop 3
	s_cmp_lg_u64 vcc, exec
	s_cselect_b64 s[98:99], -1, 0
	v_add_u32_e32 v242, s28, v144
	v_add_u32_e32 v248, s28, v155
	v_add_u32_e32 v249, v242, v147
	ds_read_b128 v[84:87], v249
	v_add_u32_e32 v251, v242, v148
	ds_read_b128 v[88:91], v251
	v_add_u32_e32 v249, v242, v149
	ds_read_b128 v[92:95], v249
	v_add_u32_e32 v251, v242, v150
	ds_read_b128 v[96:99], v251
	v_add_u32_e32 v249, v242, v151
	ds_read_b128 v[194:197], v249
	v_add_u32_e32 v251, v242, v152
	ds_read_b128 v[198:201], v251
	v_add_u32_e32 v249, v242, v153
	ds_read_b128 v[202:205], v249
	v_add_u32_e32 v251, v242, v154
	ds_read_b128 v[206:209], v251
	v_sub_f32_e32 v250, v159, v133
	s_waitcnt lgkmcnt(7)
	v_mfma_f32_32x32x16_bf16 v[68:83], v[84:87], v[100:103], v[226:241]
	v_add_u32_e32 v249, v242, v147
	ds_read_b128 v[84:87], v249 offset:8192
	s_waitcnt lgkmcnt(7)
	v_mfma_f32_32x32x16_bf16 v[68:83], v[88:91], v[104:107], v[68:83]
	v_add_u32_e32 v251, v242, v148
	ds_read_b128 v[88:91], v251 offset:8192
	s_waitcnt lgkmcnt(7)
	v_mfma_f32_32x32x16_bf16 v[68:83], v[92:95], v[108:111], v[68:83]
	v_add_u32_e32 v249, v242, v149
	ds_read_b128 v[92:95], v249 offset:8192
	s_waitcnt lgkmcnt(7)
	v_mfma_f32_32x32x16_bf16 v[68:83], v[96:99], v[112:115], v[68:83]
	v_add_u32_e32 v251, v242, v150
	ds_read_b128 v[96:99], v251 offset:8192
	s_waitcnt lgkmcnt(7)
	v_mfma_f32_32x32x16_bf16 v[68:83], v[194:197], v[116:119], v[68:83]
	v_add_u32_e32 v249, v242, v151
	ds_read_b128 v[194:197], v249 offset:8192
	s_waitcnt lgkmcnt(7)
	v_mfma_f32_32x32x16_bf16 v[68:83], v[198:201], v[120:123], v[68:83]
	v_add_u32_e32 v251, v242, v152
	ds_read_b128 v[198:201], v251 offset:8192
	s_waitcnt lgkmcnt(7)
	v_mfma_f32_32x32x16_bf16 v[68:83], v[202:205], v[124:127], v[68:83]
	v_add_u32_e32 v249, v242, v153
	ds_read_b128 v[202:205], v249 offset:8192
	s_waitcnt lgkmcnt(7)
	v_mfma_f32_32x32x16_bf16 v[68:83], v[206:209], v[128:131], v[68:83]
	v_add_u32_e32 v251, v242, v154
	ds_read_b128 v[206:209], v251 offset:8192
	s_waitcnt lgkmcnt(7)
	v_mfma_f32_32x32x16_bf16 v[210:225], v[84:87], v[100:103], v[226:241]
	ds_read_b64_tr_b16 v[84:85], v248 offset:0
	ds_read_b64_tr_b16 v[86:87], v248 offset:2048
	s_waitcnt lgkmcnt(8)
	v_mfma_f32_32x32x16_bf16 v[210:225], v[88:91], v[104:107], v[210:225]
	ds_read_b64_tr_b16 v[88:89], v248 offset:4096
	ds_read_b64_tr_b16 v[90:91], v248 offset:6144
	s_waitcnt lgkmcnt(9)
	v_mfma_f32_32x32x16_bf16 v[210:225], v[92:95], v[108:111], v[210:225]
	ds_read_b64_tr_b16 v[92:93], v248 offset:512
	ds_read_b64_tr_b16 v[94:95], v248 offset:2560
	s_waitcnt lgkmcnt(10)
	v_mfma_f32_32x32x16_bf16 v[210:225], v[96:99], v[112:115], v[210:225]
	ds_read_b64_tr_b16 v[96:97], v248 offset:4608
	ds_read_b64_tr_b16 v[98:99], v248 offset:6656
	s_waitcnt lgkmcnt(11)
	v_mfma_f32_32x32x16_bf16 v[210:225], v[194:197], v[116:119], v[210:225]
	ds_read_b64_tr_b16 v[194:195], v248 offset:1024
	ds_read_b64_tr_b16 v[196:197], v248 offset:3072
	s_waitcnt lgkmcnt(12)
	v_mfma_f32_32x32x16_bf16 v[210:225], v[198:201], v[120:123], v[210:225]
	ds_read_b64_tr_b16 v[198:199], v248 offset:5120
	ds_read_b64_tr_b16 v[200:201], v248 offset:7168
	s_waitcnt lgkmcnt(13)
	v_mfma_f32_32x32x16_bf16 v[210:225], v[202:205], v[124:127], v[210:225]
	ds_read_b64_tr_b16 v[202:203], v248 offset:1536
	ds_read_b64_tr_b16 v[204:205], v248 offset:3584
	s_waitcnt lgkmcnt(14)
	v_mfma_f32_32x32x16_bf16 v[210:225], v[206:209], v[128:131], v[210:225]
	ds_read_b64_tr_b16 v[206:207], v248 offset:5632
	ds_read_b64_tr_b16 v[208:209], v248 offset:7680
	v_fmamk_f32 v251, v132, 0x42000000, v159
	v_add_u32_e32 v249, s52, v156
	v_sub_f32_e32 v251, v251, v133
	v_add_u32_e32 v249, 0x10000, v249
	s_and_b64 vcc, exec, s[98:99]
	s_cbranch_vccz .Lpb_nm
	v_cmp_lt_i32_e32 vcc, -1, v160
	v_cmp_lt_i32_e64 s[10:11], 0, v160
	v_cmp_lt_i32_e64 s[12:13], 1, v160
	v_cmp_lt_i32_e64 s[2:3], 2, v160
	s_nop 0
	v_cndmask_b32_e32 v68, v183, v68, vcc
	v_cndmask_b32_e64 v69, v183, v69, s[10:11]
	v_cndmask_b32_e64 v70, v183, v70, s[12:13]
	v_cndmask_b32_e64 v71, v183, v71, s[2:3]
	v_cmp_lt_i32_e32 vcc, 7, v160
	v_cmp_lt_i32_e64 s[10:11], 8, v160
	v_cmp_lt_i32_e64 s[12:13], 9, v160
	v_cmp_lt_i32_e64 s[2:3], 10, v160
	s_nop 0
	v_cndmask_b32_e32 v72, v183, v72, vcc
	v_cndmask_b32_e64 v73, v183, v73, s[10:11]
	v_cndmask_b32_e64 v74, v183, v74, s[12:13]
	v_cndmask_b32_e64 v75, v183, v75, s[2:3]
	v_cmp_lt_i32_e32 vcc, 15, v160
	v_cmp_lt_i32_e64 s[10:11], 16, v160
	v_cmp_lt_i32_e64 s[12:13], 17, v160
	v_cmp_lt_i32_e64 s[2:3], 18, v160
	s_nop 0
	v_cndmask_b32_e32 v76, v183, v76, vcc
	v_cndmask_b32_e64 v77, v183, v77, s[10:11]
	v_cndmask_b32_e64 v78, v183, v78, s[12:13]
	v_cndmask_b32_e64 v79, v183, v79, s[2:3]
	v_cmp_lt_i32_e32 vcc, 23, v160
	v_cmp_lt_i32_e64 s[10:11], 24, v160
	v_cmp_lt_i32_e64 s[12:13], 25, v160
	v_cmp_lt_i32_e64 s[2:3], 26, v160
	s_nop 0
	v_cndmask_b32_e32 v80, v183, v80, vcc
	v_cndmask_b32_e64 v81, v183, v81, s[10:11]
	v_cndmask_b32_e64 v82, v183, v82, s[12:13]
	v_cndmask_b32_e64 v83, v183, v83, s[2:3]
	v_cmp_lt_i32_e32 vcc, 31, v160
	v_cmp_lt_i32_e64 s[10:11], 32, v160
	v_cmp_lt_i32_e64 s[12:13], 33, v160
	v_cmp_lt_i32_e64 s[2:3], 34, v160
	s_nop 0
	v_cndmask_b32_e32 v210, v183, v210, vcc
	v_cndmask_b32_e64 v211, v183, v211, s[10:11]
	v_cndmask_b32_e64 v212, v183, v212, s[12:13]
	v_cndmask_b32_e64 v213, v183, v213, s[2:3]
	v_cmp_lt_i32_e32 vcc, 39, v160
	v_cmp_lt_i32_e64 s[10:11], 40, v160
	v_cmp_lt_i32_e64 s[12:13], 41, v160
	v_cmp_lt_i32_e64 s[2:3], 42, v160
	s_nop 0
	v_cndmask_b32_e32 v214, v183, v214, vcc
	v_cndmask_b32_e64 v215, v183, v215, s[10:11]
	v_cndmask_b32_e64 v216, v183, v216, s[12:13]
	v_cndmask_b32_e64 v217, v183, v217, s[2:3]
	v_cmp_lt_i32_e32 vcc, 47, v160
	v_cmp_lt_i32_e64 s[10:11], 48, v160
	v_cmp_lt_i32_e64 s[12:13], 49, v160
	v_cmp_lt_i32_e64 s[2:3], 50, v160
	s_nop 0
	v_cndmask_b32_e32 v218, v183, v218, vcc
	v_cndmask_b32_e64 v219, v183, v219, s[10:11]
	v_cndmask_b32_e64 v220, v183, v220, s[12:13]
	v_cndmask_b32_e64 v221, v183, v221, s[2:3]
	v_cmp_lt_i32_e32 vcc, 55, v160
	v_cmp_lt_i32_e64 s[10:11], 56, v160
	v_cmp_lt_i32_e64 s[12:13], 57, v160
	v_cmp_lt_i32_e64 s[2:3], 58, v160
	s_nop 0
	v_cndmask_b32_e32 v222, v183, v222, vcc
	v_cndmask_b32_e64 v223, v183, v223, s[10:11]
	v_cndmask_b32_e64 v224, v183, v224, s[12:13]
	v_cndmask_b32_e64 v225, v183, v225, s[2:3]
; template <bool MASK, int H> __device__ __forceinline__ void bias_exp_half(f32x16& pz, float C, float A1, float B1, int lo, int hl, float off) {
; #pragma unroll
;   for (int r = 0; r < 16; ++r) {
;     const int c0 = (r & 3) + 8 * (r >> 2) + 32 * H;
;     float s0 = fmaf(pz[r], C, fmaf(A1, (float)c0, B1)) - off;
;     if (MASK) s0 = (c0 > lo && c0 <= hl) ? s0 : -INFINITY;
;     pz[r] = __builtin_amdgcn_exp2f(s0);
;   }
; }
; __device__ __forceinline__ void pack_half(const f32x16& pz, bf16x8& paA, bf16x8& paB) {
;     ...
;   PK4(pz, 0, paA); PK4(pz, 8, paB);
;     ...
; }
.Lpb_nm:
	v_fmamk_f32 v68, v68, 0x3e0293ee, v250
	v_fmamk_f32 v69, v69, 0x3e0293ee, v250
	v_fmamk_f32 v70, v70, 0x3e0293ee, v250
	v_fmamk_f32 v71, v71, 0x3e0293ee, v250
	v_fmamk_f32 v72, v72, 0x3e0293ee, v250
	v_fmamk_f32 v73, v73, 0x3e0293ee, v250
	v_fmamk_f32 v74, v74, 0x3e0293ee, v250
	v_fmamk_f32 v75, v75, 0x3e0293ee, v250
	v_fmamk_f32 v76, v76, 0x3e0293ee, v250
	v_fmamk_f32 v77, v77, 0x3e0293ee, v250
	v_fmamk_f32 v78, v78, 0x3e0293ee, v250
	v_fmamk_f32 v79, v79, 0x3e0293ee, v250
	v_fmamk_f32 v80, v80, 0x3e0293ee, v250
	v_fmamk_f32 v81, v81, 0x3e0293ee, v250
	v_fmamk_f32 v82, v82, 0x3e0293ee, v250
	v_fmamk_f32 v83, v83, 0x3e0293ee, v250
	v_exp_f32_e32 v68, v68
	v_exp_f32_e32 v69, v69
	v_exp_f32_e32 v70, v70
	v_exp_f32_e32 v71, v71
	v_exp_f32_e32 v72, v72
	v_exp_f32_e32 v73, v73
	v_exp_f32_e32 v74, v74
	v_exp_f32_e32 v75, v75
	v_exp_f32_e32 v76, v76
	v_exp_f32_e32 v77, v77
	v_exp_f32_e32 v78, v78
	v_exp_f32_e32 v79, v79
	v_exp_f32_e32 v80, v80
	v_exp_f32_e32 v81, v81
	v_exp_f32_e32 v82, v82
	v_exp_f32_e32 v83, v83
	s_nop 0
	v_add_f32_e32 v168, v68, v69
	v_add_f32_e32 v169, v72, v73
	v_add_f32_e32 v170, v76, v77
	v_add_f32_e32 v171, v80, v81
	v_add_f32_e32 v168, v70, v168
	v_add_f32_e32 v169, v74, v169
	v_add_f32_e32 v170, v78, v170
	v_add_f32_e32 v171, v82, v171
	v_add_f32_e32 v168, v71, v168
	v_add_f32_e32 v169, v75, v169
	v_add_f32_e32 v170, v79, v170
	v_add_f32_e32 v171, v83, v171
	v_add_f32_dpp v172, v71, v71 quad_perm:[1,0,3,2] row_mask:0xf bank_mask:0xf bound_ctrl:1
	v_add_f32_dpp v173, v75, v75 quad_perm:[1,0,3,2] row_mask:0xf bank_mask:0xf bound_ctrl:1
	v_add_f32_dpp v174, v79, v79 quad_perm:[1,0,3,2] row_mask:0xf bank_mask:0xf bound_ctrl:1
	v_add_f32_dpp v175, v83, v83 quad_perm:[1,0,3,2] row_mask:0xf bank_mask:0xf bound_ctrl:1
	v_add_f32_dpp v168, v168, v168 quad_perm:[1,0,3,2] row_mask:0xf bank_mask:0xf bound_ctrl:1
	v_add_f32_dpp v169, v169, v169 quad_perm:[1,0,3,2] row_mask:0xf bank_mask:0xf bound_ctrl:1
	v_add_f32_dpp v170, v170, v170 quad_perm:[1,0,3,2] row_mask:0xf bank_mask:0xf bound_ctrl:1
	v_add_f32_dpp v171, v171, v171 quad_perm:[1,0,3,2] row_mask:0xf bank_mask:0xf bound_ctrl:1
	v_add_f32_dpp v172, v172, v172 quad_perm:[2,3,0,1] row_mask:0xf bank_mask:0xf bound_ctrl:1
	v_add_f32_dpp v173, v173, v173 quad_perm:[2,3,0,1] row_mask:0xf bank_mask:0xf bound_ctrl:1
	v_add_f32_dpp v174, v174, v174 quad_perm:[2,3,0,1] row_mask:0xf bank_mask:0xf bound_ctrl:1
	v_add_f32_dpp v175, v175, v175 quad_perm:[2,3,0,1] row_mask:0xf bank_mask:0xf bound_ctrl:1
	v_add_f32_dpp v168, v168, v168 quad_perm:[2,3,0,1] row_mask:0xf bank_mask:0xf bound_ctrl:1
	v_add_f32_dpp v169, v169, v169 quad_perm:[2,3,0,1] row_mask:0xf bank_mask:0xf bound_ctrl:1
	v_add_f32_dpp v170, v170, v170 quad_perm:[2,3,0,1] row_mask:0xf bank_mask:0xf bound_ctrl:1
	v_add_f32_dpp v171, v171, v171 quad_perm:[2,3,0,1] row_mask:0xf bank_mask:0xf bound_ctrl:1
	s_and_saveexec_b64 s[2:3], s[8:9]
	ds_add_f32 v249, v168 offset:0
	ds_add_f32 v249, v172 offset:4
	ds_add_f32 v249, v169 offset:8
	ds_add_f32 v249, v173 offset:12
	ds_add_f32 v249, v170 offset:16
	ds_add_f32 v249, v174 offset:20
	ds_add_f32 v249, v171 offset:24
	ds_add_f32 v249, v175 offset:28
	s_or_b64 exec, exec, s[2:3]
	v_mul_f32_e32 v68, v134, v68
	v_mul_f32_e32 v69, v134, v69
	v_mul_f32_e32 v70, v134, v70
	v_mul_f32_e32 v71, v134, v71
	v_mul_f32_e32 v72, v134, v72
	v_mul_f32_e32 v73, v134, v73
	v_mul_f32_e32 v74, v134, v74
	v_mul_f32_e32 v75, v134, v75
	v_mul_f32_e32 v76, v134, v76
	v_mul_f32_e32 v77, v134, v77
	v_mul_f32_e32 v78, v134, v78
	v_mul_f32_e32 v79, v134, v79
	v_mul_f32_e32 v80, v134, v80
	v_mul_f32_e32 v81, v134, v81
	v_mul_f32_e32 v82, v134, v82
	v_mul_f32_e32 v83, v134, v83
	v_cvt_pk_bf16_f32 v168, v68, v69
	v_cvt_pk_bf16_f32 v169, v70, v71
	v_cvt_pk_bf16_f32 v170, v72, v73
	v_cvt_pk_bf16_f32 v171, v74, v75
	v_cvt_pk_bf16_f32 v172, v76, v77
	v_cvt_pk_bf16_f32 v173, v78, v79
	v_cvt_pk_bf16_f32 v174, v80, v81
	v_cvt_pk_bf16_f32 v175, v82, v83
	s_waitcnt lgkmcnt(0)
; #define SBAR() __builtin_amdgcn_sched_barrier(0)
; #define TRQ(D0) const s16x4 l0_##D0 = tr_read<v_rd_off(D0, 2 * H, 0)>(vb), h0_##D0 = tr_read<v_rd_off(D0, 2 * H, 1)>(vb), \
;                             l1_##D0 = tr_read<v_rd_off(D0, 2 * H + 1, 0)>(vb), h1_##D0 = tr_read<v_rd_off(D0, 2 * H + 1, 1)>(vb)
; template <int H> __device__ __forceinline__ void pv_half(f32x16* o, int vb, bf16x8 paA, bf16x8 paB) {
;     ...
;   TRQ(0); TRQ(1); TRQ(2); TRQ(3);
;     ...
;   asm volatile("s_waitcnt lgkmcnt(0)" ::: "memory"); SBAR();
;     ...
;   o[0] = __builtin_amdgcn_mfma_f32_32x32x16_bf16(paA, PK(l0_0, h0_0), o[0], 0, 0, 0);
;   o[1] = __builtin_amdgcn_mfma_f32_32x32x16_bf16(paA, PK(l0_1, h0_1), o[1], 0, 0, 0);
;   o[2] = __builtin_amdgcn_mfma_f32_32x32x16_bf16(paA, PK(l0_2, h0_2), o[2], 0, 0, 0);
;   o[3] = __builtin_amdgcn_mfma_f32_32x32x16_bf16(paA, PK(l0_3, h0_3), o[3], 0, 0, 0);
;   o[0] = __builtin_amdgcn_mfma_f32_32x32x16_bf16(paB, PK(l1_0, h1_0), o[0], 0, 0, 0);
;   o[1] = __builtin_amdgcn_mfma_f32_32x32x16_bf16(paB, PK(l1_1, h1_1), o[1], 0, 0, 0);
;   o[2] = __builtin_amdgcn_mfma_f32_32x32x16_bf16(paB, PK(l1_2, h1_2), o[2], 0, 0, 0);
;   o[3] = __builtin_amdgcn_mfma_f32_32x32x16_bf16(paB, PK(l1_3, h1_3), o[3], 0, 0, 0);
;     ...
; }
	s_nop 0
	v_permlane32_swap_b32_e32 v168, v170
	v_permlane32_swap_b32_e32 v169, v171
	v_permlane32_swap_b32_e32 v172, v174
	v_permlane32_swap_b32_e32 v173, v175
	s_nop 1
	v_mfma_f32_32x32x16_bf16 v[4:19], v[168:171], v[84:87], v[4:19]
	ds_read_b64_tr_b16 v[84:85], v248 offset:8192
	ds_read_b64_tr_b16 v[86:87], v248 offset:10240
	v_fmamk_f32 v210, v210, 0x3e0293ee, v251
	v_fmamk_f32 v211, v211, 0x3e0293ee, v251
	v_fmamk_f32 v212, v212, 0x3e0293ee, v251
	v_fmamk_f32 v213, v213, 0x3e0293ee, v251
	v_fmamk_f32 v214, v214, 0x3e0293ee, v251
	v_fmamk_f32 v215, v215, 0x3e0293ee, v251
	v_fmamk_f32 v216, v216, 0x3e0293ee, v251
	v_fmamk_f32 v217, v217, 0x3e0293ee, v251
	v_fmamk_f32 v218, v218, 0x3e0293ee, v251
	v_fmamk_f32 v219, v219, 0x3e0293ee, v251
	v_fmamk_f32 v220, v220, 0x3e0293ee, v251
	v_fmamk_f32 v221, v221, 0x3e0293ee, v251
	v_mfma_f32_32x32x16_bf16 v[52:67], v[168:171], v[92:95], v[52:67]
	ds_read_b64_tr_b16 v[92:93], v248 offset:8704
	ds_read_b64_tr_b16 v[94:95], v248 offset:10752
	v_fmamk_f32 v222, v222, 0x3e0293ee, v251
	v_fmamk_f32 v223, v223, 0x3e0293ee, v251
	v_fmamk_f32 v224, v224, 0x3e0293ee, v251
	v_fmamk_f32 v225, v225, 0x3e0293ee, v251
	v_exp_f32_e32 v210, v210
	v_exp_f32_e32 v211, v211
	v_exp_f32_e32 v212, v212
	v_exp_f32_e32 v213, v213
	v_exp_f32_e32 v214, v214
	v_exp_f32_e32 v215, v215
	v_exp_f32_e32 v216, v216
	v_exp_f32_e32 v217, v217
	v_mfma_f32_32x32x16_bf16 v[36:51], v[168:171], v[194:197], v[36:51]
	ds_read_b64_tr_b16 v[194:195], v248 offset:9216
	ds_read_b64_tr_b16 v[196:197], v248 offset:11264
	v_exp_f32_e32 v218, v218
	v_exp_f32_e32 v219, v219
	v_exp_f32_e32 v220, v220
	v_exp_f32_e32 v221, v221
	v_exp_f32_e32 v222, v222
	v_exp_f32_e32 v223, v223
	v_exp_f32_e32 v224, v224
	v_exp_f32_e32 v225, v225
	v_add_u32_e32 v251, s52, v156
	v_add_u32_e32 v251, 0x10000, v251
	v_add_f32_e32 v242, v210, v211
	v_add_f32_e32 v243, v214, v215
	v_mfma_f32_32x32x16_bf16 v[20:35], v[168:171], v[202:205], v[20:35]
	ds_read_b64_tr_b16 v[202:203], v248 offset:9728
	ds_read_b64_tr_b16 v[204:205], v248 offset:11776
	v_add_f32_e32 v244, v218, v219
	v_add_f32_e32 v245, v222, v223
	v_add_f32_e32 v242, v212, v242
	v_add_f32_e32 v243, v216, v243
	v_add_f32_e32 v244, v220, v244
	v_add_f32_e32 v245, v224, v245
	v_add_f32_e32 v242, v213, v242
	v_add_f32_e32 v243, v217, v243
	v_add_f32_e32 v244, v221, v244
	v_add_f32_e32 v245, v225, v245
	v_add_f32_dpp v246, v213, v213 quad_perm:[1,0,3,2] row_mask:0xf bank_mask:0xf bound_ctrl:1
	v_add_f32_dpp v247, v217, v217 quad_perm:[1,0,3,2] row_mask:0xf bank_mask:0xf bound_ctrl:1
	v_mfma_f32_32x32x16_bf16 v[4:19], v[172:175], v[88:91], v[4:19]
	ds_read_b64_tr_b16 v[88:89], v248 offset:12288
	ds_read_b64_tr_b16 v[90:91], v248 offset:14336
	v_add_f32_dpp v249, v221, v221 quad_perm:[1,0,3,2] row_mask:0xf bank_mask:0xf bound_ctrl:1
	v_add_f32_dpp v250, v225, v225 quad_perm:[1,0,3,2] row_mask:0xf bank_mask:0xf bound_ctrl:1
	v_add_f32_dpp v242, v242, v242 quad_perm:[1,0,3,2] row_mask:0xf bank_mask:0xf bound_ctrl:1
	v_add_f32_dpp v243, v243, v243 quad_perm:[1,0,3,2] row_mask:0xf bank_mask:0xf bound_ctrl:1
	v_add_f32_dpp v244, v244, v244 quad_perm:[1,0,3,2] row_mask:0xf bank_mask:0xf bound_ctrl:1
	v_add_f32_dpp v245, v245, v245 quad_perm:[1,0,3,2] row_mask:0xf bank_mask:0xf bound_ctrl:1
	v_add_f32_dpp v246, v246, v246 quad_perm:[2,3,0,1] row_mask:0xf bank_mask:0xf bound_ctrl:1
	v_add_f32_dpp v247, v247, v247 quad_perm:[2,3,0,1] row_mask:0xf bank_mask:0xf bound_ctrl:1
	v_add_f32_dpp v249, v249, v249 quad_perm:[2,3,0,1] row_mask:0xf bank_mask:0xf bound_ctrl:1
	v_add_f32_dpp v250, v250, v250 quad_perm:[2,3,0,1] row_mask:0xf bank_mask:0xf bound_ctrl:1
	v_add_f32_dpp v242, v242, v242 quad_perm:[2,3,0,1] row_mask:0xf bank_mask:0xf bound_ctrl:1
	v_add_f32_dpp v243, v243, v243 quad_perm:[2,3,0,1] row_mask:0xf bank_mask:0xf bound_ctrl:1
	v_mfma_f32_32x32x16_bf16 v[52:67], v[172:175], v[96:99], v[52:67]
	ds_read_b64_tr_b16 v[96:97], v248 offset:12800
	ds_read_b64_tr_b16 v[98:99], v248 offset:14848
	v_add_f32_dpp v244, v244, v244 quad_perm:[2,3,0,1] row_mask:0xf bank_mask:0xf bound_ctrl:1
	v_add_f32_dpp v245, v245, v245 quad_perm:[2,3,0,1] row_mask:0xf bank_mask:0xf bound_ctrl:1
	v_mul_f32_e32 v210, v134, v210
	v_mul_f32_e32 v211, v134, v211
	v_mul_f32_e32 v212, v134, v212
	v_mul_f32_e32 v213, v134, v213
	v_mul_f32_e32 v214, v134, v214
	v_mul_f32_e32 v215, v134, v215
	v_mul_f32_e32 v216, v134, v216
	v_mul_f32_e32 v217, v134, v217
	v_mul_f32_e32 v218, v134, v218
	v_mul_f32_e32 v219, v134, v219
	v_mfma_f32_32x32x16_bf16 v[36:51], v[172:175], v[198:201], v[36:51]
	ds_read_b64_tr_b16 v[198:199], v248 offset:13312
	ds_read_b64_tr_b16 v[200:201], v248 offset:15360
	v_mul_f32_e32 v220, v134, v220
	v_mul_f32_e32 v221, v134, v221
	v_mul_f32_e32 v222, v134, v222
	v_mul_f32_e32 v223, v134, v223
	v_mul_f32_e32 v224, v134, v224
	v_mul_f32_e32 v225, v134, v225
	v_cvt_pk_bf16_f32 v68, v210, v211
	v_cvt_pk_bf16_f32 v69, v212, v213
	v_cvt_pk_bf16_f32 v70, v214, v215
	v_cvt_pk_bf16_f32 v71, v216, v217
	v_cvt_pk_bf16_f32 v72, v218, v219
	v_cvt_pk_bf16_f32 v73, v220, v221
	v_mfma_f32_32x32x16_bf16 v[20:35], v[172:175], v[206:209], v[20:35]
	ds_read_b64_tr_b16 v[206:207], v248 offset:13824
	ds_read_b64_tr_b16 v[208:209], v248 offset:15872
	v_cvt_pk_bf16_f32 v74, v222, v223
	v_cvt_pk_bf16_f32 v75, v224, v225
	v_permlane32_swap_b32_e32 v68, v70
	v_permlane32_swap_b32_e32 v69, v71
	v_permlane32_swap_b32_e32 v72, v74
	v_permlane32_swap_b32_e32 v73, v75
	s_nop 1
	s_waitcnt lgkmcnt(14)
	v_mfma_f32_32x32x16_bf16 v[4:19], v[68:71], v[84:87], v[4:19]
	s_waitcnt lgkmcnt(12)
	v_mfma_f32_32x32x16_bf16 v[52:67], v[68:71], v[92:95], v[52:67]
	s_waitcnt lgkmcnt(10)
	v_mfma_f32_32x32x16_bf16 v[36:51], v[68:71], v[194:197], v[36:51]
	s_waitcnt lgkmcnt(8)
	v_mfma_f32_32x32x16_bf16 v[20:35], v[68:71], v[202:205], v[20:35]
	s_waitcnt lgkmcnt(6)
	v_mfma_f32_32x32x16_bf16 v[4:19], v[72:75], v[88:91], v[4:19]
	s_waitcnt lgkmcnt(4)
	v_mfma_f32_32x32x16_bf16 v[52:67], v[72:75], v[96:99], v[52:67]
	s_waitcnt lgkmcnt(2)
	v_mfma_f32_32x32x16_bf16 v[36:51], v[72:75], v[198:201], v[36:51]
	s_waitcnt lgkmcnt(0)
	v_mfma_f32_32x32x16_bf16 v[20:35], v[72:75], v[206:209], v[20:35]
	s_and_saveexec_b64 s[2:3], s[8:9]
	ds_add_f32 v251, v242 offset:32
	ds_add_f32 v251, v246 offset:36
	ds_add_f32 v251, v243 offset:40
	ds_add_f32 v251, v247 offset:44
	ds_add_f32 v251, v244 offset:48
	ds_add_f32 v251, v249 offset:52
	ds_add_f32 v251, v245 offset:56
	ds_add_f32 v251, v250 offset:60
	s_or_b64 exec, exec, s[2:3]
	s_add_i32 s52, s52, 64
	s_addk_i32 s26, 0x4000
	v_add_u32_e32 v157, 0xfffffc00, v157
	v_add_u32_e32 v158, 0x400, v158
	s_cmp_eq_u32 s0, s53
	s_cbranch_scc1 .LBB0_302
	s_branch .LBB0_276
